# hand-written final RMSNorm row loop: weights loaded once, next-row prefetch
# speedup vs baseline: 1.0062x; 1.0062x over previous
.LBB0_1485:
	global_load_dwordx4 v[100:103], v[2:3], off
	global_load_dwordx4 v[104:107], v[2:3], off offset:1024
	global_load_dwordx4 v[108:111], v[2:3], off offset:2048
	global_load_dwordx4 v[112:115], v[2:3], off offset:3072
	v_readfirstlane_b32 s100, v0
	s_nop 3
	s_lshl_b32 s0, s100, 12
	s_mov_b32 s1, 0
	v_lshl_add_u64 v[28:29], v[4:5], 0, s[0:1]
	global_load_dwordx4 v[50:53], v[28:29], off nt
	global_load_dwordx4 v[54:57], v[28:29], off offset:1024 nt
	global_load_dwordx4 v[58:61], v[28:29], off offset:2048 nt
	global_load_dwordx4 v[62:65], v[28:29], off offset:3072 nt
	s_waitcnt vmcnt(0)
.Lfn_loop:
	s_waitcnt vmcnt(4)
	v_mov_b32_e32 v34, v50
	v_mov_b32_e32 v35, v51
	v_mov_b32_e32 v36, v52
	v_mov_b32_e32 v37, v53
	v_mov_b32_e32 v38, v54
	v_mov_b32_e32 v39, v55
	v_mov_b32_e32 v40, v56
	v_mov_b32_e32 v41, v57
	v_mov_b32_e32 v42, v58
	v_mov_b32_e32 v43, v59
	v_mov_b32_e32 v44, v60
	v_mov_b32_e32 v45, v61
	v_mov_b32_e32 v46, v62
	v_mov_b32_e32 v47, v63
	v_mov_b32_e32 v48, v64
	v_mov_b32_e32 v49, v65
	v_mov_b32_e32 v116, v28
	v_mov_b32_e32 v117, v29
	s_add_i32 s6, s100, s4
	s_cmp_gt_i32 s6, 0x3fff
	s_cselect_b32 s7, s100, s6
	s_lshl_b32 s0, s7, 12
	s_mov_b32 s1, 0
	v_lshl_add_u64 v[28:29], v[4:5], 0, s[0:1]
	global_load_dwordx4 v[50:53], v[28:29], off nt
	global_load_dwordx4 v[54:57], v[28:29], off offset:1024 nt
	global_load_dwordx4 v[58:61], v[28:29], off offset:2048 nt
	global_load_dwordx4 v[62:65], v[28:29], off offset:3072 nt
	v_mul_f32_e32 v1, v34, v34
	v_fmac_f32_e32 v1, v35, v35
	v_fmac_f32_e32 v1, v36, v36
	v_fmac_f32_e32 v1, v37, v37
	v_fmac_f32_e32 v1, v38, v38
	v_fmac_f32_e32 v1, v39, v39
	v_fmac_f32_e32 v1, v40, v40
	v_fmac_f32_e32 v1, v41, v41
	v_fmac_f32_e32 v1, v42, v42
	v_fmac_f32_e32 v1, v43, v43
	v_fmac_f32_e32 v1, v44, v44
	v_fmac_f32_e32 v1, v45, v45
	v_fmac_f32_e32 v1, v46, v46
	v_fmac_f32_e32 v1, v47, v47
	v_fmac_f32_e32 v1, v48, v48
	v_fmac_f32_e32 v1, v49, v49
	ds_bpermute_b32 v7, v194, v1
	s_waitcnt lgkmcnt(0)
	v_add_f32_e32 v1, v1, v7
	ds_bpermute_b32 v7, v195, v1
	s_waitcnt lgkmcnt(0)
	v_add_f32_e32 v1, v1, v7
	ds_bpermute_b32 v7, v196, v1
	s_waitcnt lgkmcnt(0)
	v_add_f32_e32 v1, v1, v7
	ds_bpermute_b32 v7, v197, v1
	s_waitcnt lgkmcnt(0)
	v_add_f32_e32 v1, v1, v7
	ds_bpermute_b32 v7, v198, v1
	s_waitcnt lgkmcnt(0)
	v_add_f32_e32 v1, v1, v7
	ds_bpermute_b32 v7, v199, v1
	s_waitcnt lgkmcnt(0)
	v_add_f32_e32 v1, v1, v7
	v_fmamk_f32 v1, v1, 0x3a800000, v6
	v_mul_f32_e32 v7, 0x4b800000, v1
	v_cmp_gt_f32_e32 vcc, s2, v1
	s_nop 1
	v_cndmask_b32_e32 v1, v1, v7, vcc
	v_rsq_f32_e32 v1, v1
	s_nop 0
	v_mul_f32_e32 v7, 0x45800000, v1
	v_cndmask_b32_e32 v118, v1, v7, vcc
	v_pk_mul_f32 v[34:35], v[34:35], v[118:119] op_sel_hi:[1,0]
	v_pk_mul_f32 v[36:37], v[36:37], v[118:119] op_sel_hi:[1,0]
	v_pk_mul_f32 v[34:35], v[100:101], v[34:35]
	v_pk_mul_f32 v[36:37], v[102:103], v[36:37]
	global_store_dwordx4 v[116:117], v[34:37], off nt
	v_pk_mul_f32 v[38:39], v[38:39], v[118:119] op_sel_hi:[1,0]
	v_pk_mul_f32 v[40:41], v[40:41], v[118:119] op_sel_hi:[1,0]
	v_pk_mul_f32 v[38:39], v[104:105], v[38:39]
	v_pk_mul_f32 v[40:41], v[106:107], v[40:41]
	global_store_dwordx4 v[116:117], v[38:41], off offset:1024 nt
	v_pk_mul_f32 v[42:43], v[42:43], v[118:119] op_sel_hi:[1,0]
	v_pk_mul_f32 v[44:45], v[44:45], v[118:119] op_sel_hi:[1,0]
	v_pk_mul_f32 v[42:43], v[108:109], v[42:43]
	v_pk_mul_f32 v[44:45], v[110:111], v[44:45]
	global_store_dwordx4 v[116:117], v[42:45], off offset:2048 nt
	v_pk_mul_f32 v[46:47], v[46:47], v[118:119] op_sel_hi:[1,0]
	v_pk_mul_f32 v[48:49], v[48:49], v[118:119] op_sel_hi:[1,0]
	v_pk_mul_f32 v[46:47], v[112:113], v[46:47]
	v_pk_mul_f32 v[48:49], v[114:115], v[48:49]
	global_store_dwordx4 v[116:117], v[46:49], off offset:3072 nt
	s_cmp_gt_i32 s6, 0x3fff
	s_mov_b32 s100, s6
	s_cbranch_scc0 .Lfn_loop
